# lever 6 (LDS bank conflicts): weight-convert phases transpose 4 consecutive k per thread with ds_write_b64 (was 16 conflicting ds_write_b16), row loads issued together
# speedup vs baseline: 1.0125x; 1.0076x over previous
.LBB0_26:
	s_or_b64 exec, exec, s[86:87]
	s_waitcnt vmcnt(0)
	v_add_u32_e32 v4, s94, v18
	v_ashrrev_i32_e32 v11, 31, v4
	v_mad_u64_u32 v[4:5], s[34:35], v4, s92, 0
	v_mov_b32_e32 v6, v5
	s_waitcnt lgkmcnt(0)
	s_barrier
	ds_read_b128 v[0:3], v19
	ds_read_b128 v[26:29], v19 offset:16
	v_mad_u64_u32 v[12:13], s[34:35], v11, s92, v[6:7]
	v_mov_b32_e32 v5, v12
	v_lshl_add_u64 v[4:5], v[4:5], 1, s[12:13]
	s_ashr_i32 s89, s88, 31
	v_lshl_add_u64 v[4:5], s[88:89], 1, v[4:5]
	v_mov_b32_e32 v11, v7
	s_add_i32 s3, s3, s28
	v_lshl_add_u64 v[4:5], v[4:5], 0, v[10:11]
	s_cmpk_lt_i32 s3, 0x1220
	s_waitcnt lgkmcnt(1)
	global_store_dwordx4 v[4:5], v[0:3], off
	s_waitcnt lgkmcnt(0)
	global_store_dwordx4 v[4:5], v[26:29], off offset:16
	s_barrier
	s_cbranch_scc0 .LBB0_74

.LBB0_64:
	s_mul_i32 s35, s35, s34
	s_sub_i32 s34, s93, s35
	v_lshl_add_u64 v[0:1], v[6:7], 2, s[86:87]
	s_lshl_b32 s88, s34, 6
	v_cmp_lt_i32_e32 vcc, -1, v6
	v_lshl_add_u64 v[12:13], v[0:1], 0, v[8:9]
	v_mov_b32_e32 v2, 0
	v_mov_b32_e32 v3, 0
	v_mov_b32_e32 v4, 0
	v_mov_b32_e32 v5, 0
	v_mov_b32_e32 v200, 0
	v_mov_b32_e32 v201, 0
	v_mov_b32_e32 v202, 0
	v_mov_b32_e32 v203, 0
	v_mov_b32_e32 v204, 0
	v_mov_b32_e32 v205, 0
	v_mov_b32_e32 v206, 0
	v_mov_b32_e32 v207, 0
	v_mov_b32_e32 v208, 0
	v_mov_b32_e32 v209, 0
	v_mov_b32_e32 v210, 0
	v_mov_b32_e32 v211, 0
	s_and_saveexec_b64 s[86:87], vcc
	s_cbranch_execz .Lcv_x_0
	v_lshl_add_u32 v212, v14, 2, s88
	v_ashrrev_i32_e32 v213, 31, v212
	v_mul_lo_u32 v214, s84, v213
	v_mul_lo_u32 v215, s85, v212
	v_mad_u64_u32 v[216:217], s[34:35], s84, v212, 0
	v_add3_u32 v217, v217, v214, v215
	v_lshl_add_u64 v[216:217], v[216:217], 2, v[12:13]
	global_load_dwordx4 v[2:5], v[216:217], off nt
	v_lshl_add_u32 v212, v14, 2, s88
	v_add_u32_e32 v212, 1, v212
	v_ashrrev_i32_e32 v213, 31, v212
	v_mul_lo_u32 v214, s84, v213
	v_mul_lo_u32 v215, s85, v212
	v_mad_u64_u32 v[216:217], s[34:35], s84, v212, 0
	v_add3_u32 v217, v217, v214, v215
	v_lshl_add_u64 v[216:217], v[216:217], 2, v[12:13]
	global_load_dwordx4 v[200:203], v[216:217], off nt
	v_lshl_add_u32 v212, v14, 2, s88
	v_add_u32_e32 v212, 2, v212
	v_ashrrev_i32_e32 v213, 31, v212
	v_mul_lo_u32 v214, s84, v213
	v_mul_lo_u32 v215, s85, v212
	v_mad_u64_u32 v[216:217], s[34:35], s84, v212, 0
	v_add3_u32 v217, v217, v214, v215
	v_lshl_add_u64 v[216:217], v[216:217], 2, v[12:13]
	global_load_dwordx4 v[204:207], v[216:217], off nt
	v_lshl_add_u32 v212, v14, 2, s88
	v_add_u32_e32 v212, 3, v212
	v_ashrrev_i32_e32 v213, 31, v212
	v_mul_lo_u32 v214, s84, v213
	v_mul_lo_u32 v215, s85, v212
	v_mad_u64_u32 v[216:217], s[34:35], s84, v212, 0
	v_add3_u32 v217, v217, v214, v215
	v_lshl_add_u64 v[216:217], v[216:217], 2, v[12:13]
	global_load_dwordx4 v[208:211], v[216:217], off nt
.Lcv_x_0:
	s_or_b64 exec, exec, s[86:87]
	v_mul_u32_u24_e32 v226, 6, v14
	v_add_u32_e32 v226, v20, v226
	s_waitcnt vmcnt(0)
	v_cvt_pk_f16_f32 v218, v2, v200
	v_cvt_pk_f16_f32 v219, v204, v208
	v_cvt_pk_f16_f32 v220, v3, v201
	v_cvt_pk_f16_f32 v221, v205, v209
	v_cvt_pk_f16_f32 v222, v4, v202
	v_cvt_pk_f16_f32 v223, v206, v210
	v_cvt_pk_f16_f32 v224, v5, v203
	v_cvt_pk_f16_f32 v225, v207, v211
	ds_write_b64 v226, v[218:219]
	ds_write_b64 v226, v[220:221] offset:144
	ds_write_b64 v226, v[222:223] offset:288
	ds_write_b64 v226, v[224:225] offset:432
	s_branch .LBB0_26

.LBB0_1016:
	s_or_b64 exec, exec, s[52:53]
	s_waitcnt vmcnt(0)
	v_add_u32_e32 v4, s84, v18
	v_ashrrev_i32_e32 v11, 31, v4
	v_mad_u64_u32 v[4:5], s[26:27], v4, s68, 0
	v_mov_b32_e32 v6, v5
	s_waitcnt lgkmcnt(0)
	s_barrier
	ds_read_b128 v[0:3], v19
	ds_read_b128 v[26:29], v19 offset:16
	v_mad_u64_u32 v[12:13], s[26:27], v11, s68, v[6:7]
	v_mov_b32_e32 v5, v12
	v_lshl_add_u64 v[4:5], v[4:5], 1, s[24:25]
	s_ashr_i32 s57, s56, 31
	v_lshl_add_u64 v[4:5], s[56:57], 1, v[4:5]
	v_mov_b32_e32 v11, v7
	s_add_i32 s3, s3, s28
	v_lshl_add_u64 v[4:5], v[4:5], 0, v[10:11]
	s_cmpk_lt_i32 s3, 0x1220
	s_waitcnt lgkmcnt(1)
	global_store_dwordx4 v[4:5], v[0:3], off
	s_waitcnt lgkmcnt(0)
	global_store_dwordx4 v[4:5], v[26:29], off offset:16
	s_barrier
	s_cbranch_scc0 .LBB0_1064

.LBB0_1055:
	s_mul_i32 s35, s35, s34
	s_sub_i32 s34, s69, s35
	v_lshl_add_u64 v[0:1], v[6:7], 2, s[52:53]
	s_lshl_b32 s56, s34, 6
	v_cmp_lt_i32_e32 vcc, -1, v6
	v_lshl_add_u64 v[12:13], v[0:1], 0, v[8:9]
	v_mov_b32_e32 v2, 0
	v_mov_b32_e32 v3, 0
	v_mov_b32_e32 v4, 0
	v_mov_b32_e32 v5, 0
	v_mov_b32_e32 v200, 0
	v_mov_b32_e32 v201, 0
	v_mov_b32_e32 v202, 0
	v_mov_b32_e32 v203, 0
	v_mov_b32_e32 v204, 0
	v_mov_b32_e32 v205, 0
	v_mov_b32_e32 v206, 0
	v_mov_b32_e32 v207, 0
	v_mov_b32_e32 v208, 0
	v_mov_b32_e32 v209, 0
	v_mov_b32_e32 v210, 0
	v_mov_b32_e32 v211, 0
	s_and_saveexec_b64 s[52:53], vcc
	s_cbranch_execz .Lcv_x_1
	v_lshl_add_u32 v212, v14, 2, s56
	v_ashrrev_i32_e32 v213, 31, v212
	v_mul_lo_u32 v214, s26, v213
	v_mul_lo_u32 v215, s27, v212
	v_mad_u64_u32 v[216:217], s[34:35], s26, v212, 0
	v_add3_u32 v217, v217, v214, v215
	v_lshl_add_u64 v[216:217], v[216:217], 2, v[12:13]
	global_load_dwordx4 v[2:5], v[216:217], off nt
	v_lshl_add_u32 v212, v14, 2, s56
	v_add_u32_e32 v212, 1, v212
	v_ashrrev_i32_e32 v213, 31, v212
	v_mul_lo_u32 v214, s26, v213
	v_mul_lo_u32 v215, s27, v212
	v_mad_u64_u32 v[216:217], s[34:35], s26, v212, 0
	v_add3_u32 v217, v217, v214, v215
	v_lshl_add_u64 v[216:217], v[216:217], 2, v[12:13]
	global_load_dwordx4 v[200:203], v[216:217], off nt
	v_lshl_add_u32 v212, v14, 2, s56
	v_add_u32_e32 v212, 2, v212
	v_ashrrev_i32_e32 v213, 31, v212
	v_mul_lo_u32 v214, s26, v213
	v_mul_lo_u32 v215, s27, v212
	v_mad_u64_u32 v[216:217], s[34:35], s26, v212, 0
	v_add3_u32 v217, v217, v214, v215
	v_lshl_add_u64 v[216:217], v[216:217], 2, v[12:13]
	global_load_dwordx4 v[204:207], v[216:217], off nt
	v_lshl_add_u32 v212, v14, 2, s56
	v_add_u32_e32 v212, 3, v212
	v_ashrrev_i32_e32 v213, 31, v212
	v_mul_lo_u32 v214, s26, v213
	v_mul_lo_u32 v215, s27, v212
	v_mad_u64_u32 v[216:217], s[34:35], s26, v212, 0
	v_add3_u32 v217, v217, v214, v215
	v_lshl_add_u64 v[216:217], v[216:217], 2, v[12:13]
	global_load_dwordx4 v[208:211], v[216:217], off nt
.Lcv_x_1:
	s_or_b64 exec, exec, s[52:53]
	v_mul_u32_u24_e32 v226, 6, v14
	v_add_u32_e32 v226, v20, v226
	s_waitcnt vmcnt(0)
	v_cvt_pk_f16_f32 v218, v2, v200
	v_cvt_pk_f16_f32 v219, v204, v208
	v_cvt_pk_f16_f32 v220, v3, v201
	v_cvt_pk_f16_f32 v221, v205, v209
	v_cvt_pk_f16_f32 v222, v4, v202
	v_cvt_pk_f16_f32 v223, v206, v210
	v_cvt_pk_f16_f32 v224, v5, v203
	v_cvt_pk_f16_f32 v225, v207, v211
	ds_write_b64 v226, v[218:219]
	ds_write_b64 v226, v[220:221] offset:144
	ds_write_b64 v226, v[222:223] offset:288
	ds_write_b64 v226, v[224:225] offset:432
	s_branch .LBB0_1016
